# code placement: ff1/ff2 K-loop heads shifted by 4 bytes back to the baseline's byte phase (mod 8)
# baseline (speedup 1.0000x reference)
.LBB0_2116:
	s_or_b64 exec, exec, s[6:7]
	v_readlane_b32 s0, v254, 41
	s_mov_b64 s[6:7], s[40:41]
	v_mov_b32_e32 v14, v228
	v_readlane_b32 s1, v254, 42
	s_xor_b64 s[14:15], s[14:15], -1
	s_waitcnt lgkmcnt(0)
	s_barrier
	s_lshl_b64 s[16:17], s[74:75], 23
	s_andn2_b64 vcc, exec, s[0:1]
	v_readfirstlane_b32 s8, v14
	s_cbranch_vccnz .LBB0_2132
	s_nop 0
	v_lshlrev_b32_e32 v0, 4, v14
	v_add_u32_e32 v1, 0x2000, v0
	v_ashrrev_i32_e32 v2, 31, v1
	v_lshrrev_b32_e32 v2, 22, v2
	v_add_u32_e32 v2, v1, v2
	v_ashrrev_i32_e32 v8, 10, v2
	v_mul_i32_i24_e32 v2, 0x400, v8
	v_sub_u32_e32 v1, v1, v2
	v_lshrrev_b32_e32 v2, 4, v1
	v_bitop3_b32 v1, v2, v1, 32 bitop3:0x6c
	v_ashrrev_i32_e32 v2, 31, v1
	s_add_u32 s33, s6, 0x9600000
	v_lshrrev_b32_e32 v2, 26, v2
	s_addc_u32 s44, s7, 0
	v_add_u32_e32 v2, v1, v2
	v_lshlrev_b32_e32 v3, 3, v8
	s_add_u32 s0, s6, s16
	v_ashrrev_i32_e32 v9, 6, v2
	v_and_b32_e32 v3, -16, v3
	s_addc_u32 s1, s7, s17
	v_add_u32_e32 v3, v9, v3
	s_add_u32 s45, s0, 0x2600000
	v_and_b32_e32 v4, 3, v9
	s_mov_b32 s0, 0x1fffe0
	v_lshrrev_b32_e32 v5, 2, v3
	v_lshlrev_b32_e32 v6, 1, v3
	v_and_b32_e32 v2, 0xc0, v2
	v_and_or_b32 v4, v3, s0, v4
	v_and_b32_e32 v5, 4, v5
	v_and_b32_e32 v6, 24, v6
	v_sub_u32_e32 v1, v1, v2
	v_or3_b32 v4, v4, v5, v6
	v_lshlrev_b32_e32 v5, 5, v8
	v_ashrrev_i16_sdwa v1, v230, sext(v1) dst_sel:DWORD dst_unused:UNUSED_PAD src0_sel:DWORD src1_sel:BYTE_0
	v_and_b32_e32 v5, 32, v5
	v_bfe_i32 v10, v1, 0, 16
	v_add_lshl_u32 v1, v5, v10, 1
	v_lshl_add_u32 v146, v4, 11, v1
	v_lshl_add_u32 v148, v3, 11, v1
	v_bfe_i32 v1, v14, 27, 1
	v_lshrrev_b32_e32 v1, 22, v1
	v_add_u32_e32 v1, v0, v1
	v_and_b32_e32 v1, 0xfffffc00, v1
	v_sub_u32_e32 v0, v0, v1
	v_lshrrev_b32_e32 v1, 4, v0
	v_ashrrev_i32_e32 v2, 31, v14
	v_bitop3_b32 v0, v1, v0, 32 bitop3:0x6c
	v_lshrrev_b32_e32 v2, 26, v2
	v_ashrrev_i32_e32 v1, 31, v0
	v_add_u32_e32 v2, v14, v2
	v_lshrrev_b32_e32 v1, 26, v1
	v_ashrrev_i32_e32 v12, 6, v2
	v_add_u32_e32 v1, v0, v1
	v_lshlrev_b32_e32 v2, 3, v12
	v_ashrrev_i32_e32 v11, 6, v1
	v_and_b32_e32 v2, -16, v2
	v_add_u32_e32 v2, v11, v2
	v_and_b32_e32 v3, 3, v11
	v_lshrrev_b32_e32 v4, 2, v2
	v_lshlrev_b32_e32 v5, 1, v2
	v_and_b32_e32 v1, 0xc0, v1
	s_addc_u32 s53, s1, 0
	s_ashr_i32 s4, s8, 6
	v_and_or_b32 v3, v2, s0, v3
	v_and_b32_e32 v4, 4, v4
	v_and_b32_e32 v5, 24, v5
	v_sub_u32_e32 v0, v0, v1
	s_ashr_i32 s5, s8, 8
	s_lshl_b32 s60, s4, 10
	v_or3_b32 v3, v3, v4, v5
	v_lshlrev_b32_e32 v4, 5, v12
	v_ashrrev_i16_sdwa v0, v230, sext(v0) dst_sel:DWORD dst_unused:UNUSED_PAD src0_sel:DWORD src1_sel:BYTE_0
	v_readlane_b32 s0, v254, 60
	v_and_b32_e32 v4, 32, v4
	v_bfe_i32 v13, v0, 0, 16
	v_readlane_b32 s1, v254, 61
	s_add_u32 s34, s45, s0
	v_add_lshl_u32 v0, v4, v13, 1
	s_addc_u32 s35, s53, s1
	s_add_i32 s61, s60, 0
	v_lshl_add_u32 v64, v3, 11, v0
	s_add_i32 m0, s61, 0x10000
	v_lshl_add_u32 v150, v2, 11, v0
	global_load_lds_dwordx4 v64, s[34:35]
	s_add_i32 m0, s61, 0x12000
	s_add_u32 s0, s34, 0x40000
	global_load_lds_dwordx4 v146, s[34:35]
	s_addc_u32 s1, s35, 0
	s_add_i32 m0, s61, 0x14000
	v_mov_b32_e32 v147, v65
	global_load_lds_dwordx4 v64, s[0:1]
	s_add_i32 m0, s61, 0x16000
	v_mov_b32_e32 v151, v65
	global_load_lds_dwordx4 v146, s[0:1]
	v_readlane_b32 s0, v254, 58
	v_readlane_b32 s1, v254, 59
	s_add_u32 s56, s33, s0
	s_addc_u32 s57, s44, s1
	s_add_i32 s63, s61, 0x2000
	s_mov_b32 m0, s61
	s_add_u32 s0, s56, 0x40000
	global_load_lds_dwordx4 v150, s[56:57]
	s_mov_b32 m0, s63
	s_addc_u32 s1, s57, 0
	s_add_i32 s75, s61, 0x4000
	global_load_lds_dwordx4 v148, s[56:57]
	s_mov_b32 m0, s75
	s_add_i32 s79, s61, 0x6000
	global_load_lds_dwordx4 v150, s[0:1]
	s_mov_b32 m0, s79
	v_mov_b32_e32 v149, v65
	global_load_lds_dwordx4 v148, s[0:1]
	s_cmp_eq_u32 s5, 1
	v_lshl_add_u64 v[6:7], s[34:35], 0, v[64:65]
	v_lshl_add_u64 v[4:5], s[34:35], 0, v[146:147]
	v_lshl_add_u64 v[0:1], s[56:57], 0, v[150:151]
	s_cselect_b64 s[18:19], -1, 0
	s_cmp_lg_u32 s5, 1
	v_lshl_add_u64 v[2:3], s[56:57], 0, v[148:149]
	s_cbranch_scc1 .LBB0_2119
	s_barrier
